# v84 + hand-offs issue their L1 invalidate on arrival (wave 0, before draining stores and the workgroup-internal barrier) instead of after the arrival atomic
# baseline (speedup 1.0000x reference)
; __device__ __forceinline__ unsigned xb_add(unsigned* p, unsigned v) { return __hip_atomic_fetch_add(p, v, __ATOMIC_RELAXED, __HIP_MEMORY_SCOPE_AGENT); }
; __device__ __forceinline__ void xcd_barrier(const XcdBarrier& b, int tid) {
;     asm volatile("s_waitcnt vmcnt(0)" ::: "memory");
;     __syncthreads();
;     if (tid == 0) {
;         unsigned* bar = b.bar;
;         __builtin_amdgcn_s_waitcnt(0);
;         unsigned nloc = b.st[0], nx = b.st[1];
;         if (nloc == 0u) { xcd_barrier_complete(bar, b.x, nloc, nx); b.st[0] = nloc; b.st[1] = nx; }
;         const unsigned old = xb_add(&bar[XB_XSUB(b.x)], 1u);
;         const unsigned gen = old / nloc;
;         if (old + 1u == (gen + 1u) * nloc) {
;             __builtin_amdgcn_fence(__ATOMIC_RELEASE, "agent");
;             asm volatile("s_waitcnt vmcnt(0)" ::: "memory");
;             const unsigned og = xb_add(&bar[XB_TOP], 1u);
;             const unsigned tg = og / nx;
;             if (og + 1u == (tg + 1u) * nx) xb_add(&bar[XB_TOPGEN], 1u);
.LBB0_254:
	v_readlane_b32 s0, v254, 2
	s_add_i32 s4, s0, 1
	s_cmp_ge_i32 s4, s81
	s_cbranch_scc1 .LBB0_362
	v_readlane_b32 s100, v255, 57
	s_cmp_lg_u32 s100, 0
	s_cbranch_scc0 .Lgq_orig_win
	v_readfirstlane_b32 s6, v215
	s_cmp_lt_u32 s6, 64
	s_cbranch_scc0 .Lei_0
	buffer_inv sc1
.Lei_0:
	s_waitcnt vmcnt(0) lgkmcnt(0)
	s_barrier
	v_readlane_b32 s100, v255, 59
	s_add_i32 s100, s100, 1
	v_writelane_b32 v255, s100, 59
	v_cmp_eq_u32_e32 vcc, 0, v215
	s_and_saveexec_b64 s[0:1], vcc
	s_cbranch_execz .Lgq_w_win
	s_load_dwordx2 s[2:3], s[94:95], 0xb8
	v_readlane_b32 s101, v255, 12
	s_and_b32 s101, s101, 63
	s_lshl_b32 s101, s101, 6
	s_cmp_lt_u32 s101, 0x800
	s_movk_i32 s7, 0x1400
	s_cselect_b32 s7, 0xc00, s7
	s_add_i32 s101, s101, s7
	s_lshl_b32 s100, s100, 2
	v_mov_b32_e32 v0, s101
	v_mov_b32_e32 v1, 1
	s_waitcnt lgkmcnt(0)
	s_add_u32 s2, s2, 0xe0000
	s_addc_u32 s3, s3, 0
	global_atomic_add v0, v1, s[2:3]
	s_mov_b32 s6, 0

; __device__ __forceinline__ unsigned xb_add(unsigned* p, unsigned v) { return __hip_atomic_fetch_add(p, v, __ATOMIC_RELAXED, __HIP_MEMORY_SCOPE_AGENT); }
; __device__ __forceinline__ void xcd_barrier(const XcdBarrier& b, int tid) {
;     asm volatile("s_waitcnt vmcnt(0)" ::: "memory");
;     __syncthreads();
;     if (tid == 0) {
;         unsigned* bar = b.bar;
;         __builtin_amdgcn_s_waitcnt(0);
;         unsigned nloc = b.st[0], nx = b.st[1];
;         if (nloc == 0u) { xcd_barrier_complete(bar, b.x, nloc, nx); b.st[0] = nloc; b.st[1] = nx; }
;         const unsigned old = xb_add(&bar[XB_XSUB(b.x)], 1u);
;         const unsigned gen = old / nloc;
;         if (old + 1u == (gen + 1u) * nloc) {
;             __builtin_amdgcn_fence(__ATOMIC_RELEASE, "agent");
.LBB0_376:
	v_readlane_b32 s0, v254, 2
	s_add_i32 s4, s0, 2
	s_cmp_lt_i32 s4, s81
	s_cbranch_scc0 .LBB0_442
	v_readlane_b32 s100, v255, 57
	s_cmp_lg_u32 s100, 0
	s_cbranch_scc0 .Lgq_orig_gate
	v_readfirstlane_b32 s6, v215
	s_cmp_lt_u32 s6, 64
	s_cbranch_scc0 .Lei_1
	buffer_inv sc1

; __device__ __forceinline__ unsigned xb_add(unsigned* p, unsigned v) { return __hip_atomic_fetch_add(p, v, __ATOMIC_RELAXED, __HIP_MEMORY_SCOPE_AGENT); }
; __device__ __forceinline__ void xcd_barrier(const XcdBarrier& b, int tid) {
;     asm volatile("s_waitcnt vmcnt(0)" ::: "memory");
;     __syncthreads();
;     if (tid == 0) {
;         unsigned* bar = b.bar;
;         __builtin_amdgcn_s_waitcnt(0);
;         unsigned nloc = b.st[0], nx = b.st[1];
;         if (nloc == 0u) { xcd_barrier_complete(bar, b.x, nloc, nx); b.st[0] = nloc; b.st[1] = nx; }
;         const unsigned old = xb_add(&bar[XB_XSUB(b.x)], 1u);
;         const unsigned gen = old / nloc;
;         if (old + 1u == (gen + 1u) * nloc) {
;             __builtin_amdgcn_fence(__ATOMIC_RELEASE, "agent");
.LBB0_487:
	v_readlane_b32 s0, v254, 2
	s_add_i32 s74, s0, 3
	s_cmp_ge_i32 s74, s81
	s_cbranch_scc1 .LBB0_553
	v_readfirstlane_b32 s6, v215
	s_cmp_lt_u32 s6, 64
	s_cbranch_scc0 .Lei_2
	buffer_inv sc1

; __device__ __forceinline__ unsigned xb_add(unsigned* p, unsigned v) { return __hip_atomic_fetch_add(p, v, __ATOMIC_RELAXED, __HIP_MEMORY_SCOPE_AGENT); }
; __device__ __forceinline__ void xcd_barrier(const XcdBarrier& b, int tid) {
;     asm volatile("s_waitcnt vmcnt(0)" ::: "memory");
;     __syncthreads();
;     if (tid == 0) {
;         unsigned* bar = b.bar;
;         __builtin_amdgcn_s_waitcnt(0);
;         unsigned nloc = b.st[0], nx = b.st[1];
;         if (nloc == 0u) { xcd_barrier_complete(bar, b.x, nloc, nx); b.st[0] = nloc; b.st[1] = nx; }
;         const unsigned old = xb_add(&bar[XB_XSUB(b.x)], 1u);
;         const unsigned gen = old / nloc;
;         if (old + 1u == (gen + 1u) * nloc) {
;             __builtin_amdgcn_fence(__ATOMIC_RELEASE, "agent");
;             asm volatile("s_waitcnt vmcnt(0)" ::: "memory");
;             const unsigned og = xb_add(&bar[XB_TOP], 1u);
;             const unsigned tg = og / nx;
;             if (og + 1u == (tg + 1u) * nx) xb_add(&bar[XB_TOPGEN], 1u);
.LBB0_1043:
	v_readlane_b32 s0, v254, 2
	s_add_i32 s4, s0, 2
	s_cmp_lt_i32 s4, s81
	s_cbranch_scc0 .LBB0_1109
	v_readfirstlane_b32 s6, v215
	s_cmp_lt_u32 s6, 64
	s_cbranch_scc0 .Lei_3
	buffer_inv sc1
.Lei_3:
	s_waitcnt vmcnt(0) lgkmcnt(0)
	s_barrier
	v_cmp_eq_u32_e32 vcc, 0, v215
	s_and_saveexec_b64 s[0:1], vcc
	s_cbranch_execz .Lp2p_w
	s_load_dwordx2 s[2:3], s[94:95], 0xb8
	v_readlane_b32 s101, v255, 12
	s_bfe_u32 s100, s101, 0x10002
	s_lshl_b32 s100, s100, 5
	s_lshr_b32 s6, s101, 3
	s_add_i32 s100, s100, s6
	s_lshl_b32 s100, s100, 5
	s_add_i32 s100, s100, 0x2c00
	s_and_b32 s6, s101, 7
	s_lshl_b32 s6, s6, 3
	s_bfe_u32 s7, s101, 0x30003
	s_add_i32 s6, s6, s7
	s_lshl_b32 s6, s6, 5
	s_add_i32 s6, s6, 0x2c00
	v_mov_b32_e32 v0, s100
	v_mov_b32_e32 v1, 1
	v_mov_b32_e32 v3, s6
	s_waitcnt lgkmcnt(0)
	s_add_u32 s2, s2, 0xe0000
	s_addc_u32 s3, s3, 0
	global_atomic_add v0, v1, s[2:3]
	v_mov_b32_e32 v4, 0x2c10
	global_atomic_add v4, v1, s[2:3]
	s_mov_b32 s6, 0

; __device__ __forceinline__ unsigned xb_add(unsigned* p, unsigned v) { return __hip_atomic_fetch_add(p, v, __ATOMIC_RELAXED, __HIP_MEMORY_SCOPE_AGENT); }
; __device__ __forceinline__ void xcd_barrier(const XcdBarrier& b, int tid) {
;     asm volatile("s_waitcnt vmcnt(0)" ::: "memory");
;     __syncthreads();
;     if (tid == 0) {
;         unsigned* bar = b.bar;
;         __builtin_amdgcn_s_waitcnt(0);
;         unsigned nloc = b.st[0], nx = b.st[1];
;         if (nloc == 0u) { xcd_barrier_complete(bar, b.x, nloc, nx); b.st[0] = nloc; b.st[1] = nx; }
;         const unsigned old = xb_add(&bar[XB_XSUB(b.x)], 1u);
;         const unsigned gen = old / nloc;
;         if (old + 1u == (gen + 1u) * nloc) {
;             __builtin_amdgcn_fence(__ATOMIC_RELEASE, "agent");
;             asm volatile("s_waitcnt vmcnt(0)" ::: "memory");
;             const unsigned og = xb_add(&bar[XB_TOP], 1u);
;             const unsigned tg = og / nx;
;             if (og + 1u == (tg + 1u) * nx) xb_add(&bar[XB_TOPGEN], 1u);
.LBB0_1289:
	v_readlane_b32 s0, v254, 2
	s_add_i32 s4, s0, 1
	s_cmp_lt_i32 s4, s81
	s_cbranch_scc0 .LBB0_1372
	v_readlane_b32 s100, v255, 8
	s_cmp_eq_u32 s100, 3
	s_cbranch_scc0 .Lp3_orig_2
	v_readfirstlane_b32 s6, v215
	s_cmp_lt_u32 s6, 64
	s_cbranch_scc0 .Lei_5
	buffer_inv sc1
.Lei_5:
	s_waitcnt vmcnt(0) lgkmcnt(0)
	s_barrier
	v_readlane_b32 s100, v255, 59
	s_add_i32 s100, s100, 1
	v_writelane_b32 v255, s100, 59
	v_cmp_eq_u32_e32 vcc, 0, v215
	s_and_saveexec_b64 s[0:1], vcc
	s_cbranch_execz .Lp3_w_2
	s_load_dwordx2 s[2:3], s[94:95], 0xb8
	s_lshl_b32 s100, s100, 2
	v_readlane_b32 s101, v255, 12
	s_and_b32 s6, s101, 63
	s_lshl_b32 s6, s6, 6
	s_cmp_lt_u32 s6, 0x800
	s_movk_i32 s7, 0x1400
	s_cselect_b32 s7, 0xc00, s7
	s_add_i32 s6, s6, s7
	v_mov_b32_e32 v0, s6
	v_mov_b32_e32 v1, 1
	s_and_b32 s6, s101, 7
	s_lshl_b32 s6, s6, 3
	s_bfe_u32 s7, s101, 0x30003
	s_add_i32 s101, s6, s7
	s_sub_i32 s6, s101, 1
	s_max_i32 s6, s6, 0
	s_lshr_b32 s7, s6, 3
	s_and_b32 s6, s6, 7
	s_lshl_b32 s6, s6, 3
	s_add_i32 s6, s6, s7
	s_lshl_b32 s6, s6, 6
	s_cmp_lt_u32 s6, 0x800
	s_movk_i32 s7, 0x1400
	s_cselect_b32 s7, 0xc00, s7
	s_add_i32 s6, s6, s7
	v_mov_b32_e32 v3, s6
	s_add_i32 s6, s101, 1
	s_min_i32 s6, s6, 63
	s_lshr_b32 s7, s6, 3
	s_and_b32 s6, s6, 7
	s_lshl_b32 s6, s6, 3
	s_add_i32 s6, s6, s7
	s_lshl_b32 s6, s6, 6
	s_cmp_lt_u32 s6, 0x800
	s_movk_i32 s7, 0x1400
	s_cselect_b32 s7, 0xc00, s7
	s_add_i32 s6, s6, s7
	v_mov_b32_e32 v4, s6
	s_waitcnt lgkmcnt(0)
	s_add_u32 s2, s2, 0xe0000
	s_addc_u32 s3, s3, 0
	global_atomic_add v0, v1, s[2:3]
	s_mov_b32 s6, 0

; __device__ __forceinline__ unsigned xb_add(unsigned* p, unsigned v) { return __hip_atomic_fetch_add(p, v, __ATOMIC_RELAXED, __HIP_MEMORY_SCOPE_AGENT); }
; __device__ __forceinline__ void xcd_barrier(const XcdBarrier& b, int tid) {
;     asm volatile("s_waitcnt vmcnt(0)" ::: "memory");
;     __syncthreads();
;     if (tid == 0) {
;         unsigned* bar = b.bar;
;         __builtin_amdgcn_s_waitcnt(0);
;         unsigned nloc = b.st[0], nx = b.st[1];
;         if (nloc == 0u) { xcd_barrier_complete(bar, b.x, nloc, nx); b.st[0] = nloc; b.st[1] = nx; }
;         const unsigned old = xb_add(&bar[XB_XSUB(b.x)], 1u);
;         const unsigned gen = old / nloc;
;         if (old + 1u == (gen + 1u) * nloc) {
;             __builtin_amdgcn_fence(__ATOMIC_RELEASE, "agent");
.LBB0_1598:
	v_readlane_b32 s0, v254, 2
	s_add_i32 s74, s0, 2
	s_cmp_ge_i32 s74, s81
	s_cbranch_scc1 .LBB0_1681
	v_readlane_b32 s100, v255, 8
	s_cmp_eq_u32 s100, 3
	s_cbranch_scc0 .Lgs_orig_3
	v_readfirstlane_b32 s6, v215
	s_cmp_lt_u32 s6, 64
	s_cbranch_scc0 .Lei_6
	buffer_inv sc1

; __device__ __forceinline__ unsigned xb_add(unsigned* p, unsigned v) { return __hip_atomic_fetch_add(p, v, __ATOMIC_RELAXED, __HIP_MEMORY_SCOPE_AGENT); }
; __device__ __forceinline__ void xcd_barrier(const XcdBarrier& b, int tid) {
;     asm volatile("s_waitcnt vmcnt(0)" ::: "memory");
;     __syncthreads();
;     if (tid == 0) {
;         unsigned* bar = b.bar;
;         __builtin_amdgcn_s_waitcnt(0);
;         unsigned nloc = b.st[0], nx = b.st[1];
;         if (nloc == 0u) { xcd_barrier_complete(bar, b.x, nloc, nx); b.st[0] = nloc; b.st[1] = nx; }
;         const unsigned old = xb_add(&bar[XB_XSUB(b.x)], 1u);
;         const unsigned gen = old / nloc;
;         if (old + 1u == (gen + 1u) * nloc) {
;             __builtin_amdgcn_fence(__ATOMIC_RELEASE, "agent");
.LBB0_1776:
	s_add_i32 s4, s74, 1
	s_cmp_ge_i32 s4, s81
	s_cbranch_scc1 .LBB0_1842
	v_readlane_b32 s100, v255, 8
	s_cmp_lg_u32 s100, 0
	s_cbranch_scc0 .Lgs_orig_4
	v_readfirstlane_b32 s6, v215
	s_cmp_lt_u32 s6, 64
	s_cbranch_scc0 .Lei_7
	buffer_inv sc1

; __device__ __forceinline__ unsigned xb_add(unsigned* p, unsigned v) { return __hip_atomic_fetch_add(p, v, __ATOMIC_RELAXED, __HIP_MEMORY_SCOPE_AGENT); }
; __device__ __forceinline__ void xcd_barrier(const XcdBarrier& b, int tid) {
;     asm volatile("s_waitcnt vmcnt(0)" ::: "memory");
;     __syncthreads();
;     if (tid == 0) {
;         unsigned* bar = b.bar;
;         __builtin_amdgcn_s_waitcnt(0);
;         unsigned nloc = b.st[0], nx = b.st[1];
;         if (nloc == 0u) { xcd_barrier_complete(bar, b.x, nloc, nx); b.st[0] = nloc; b.st[1] = nx; }
;         const unsigned old = xb_add(&bar[XB_XSUB(b.x)], 1u);
;         const unsigned gen = old / nloc;
;         if (old + 1u == (gen + 1u) * nloc) {
;             __builtin_amdgcn_fence(__ATOMIC_RELEASE, "agent");
.LBB0_2087:
	v_readlane_b32 s100, v255, 8
	s_bitcmp1_b32 s100, 0
	s_cbranch_scc0 .Lgs_orig_5
	v_readfirstlane_b32 s6, v215
	s_cmp_lt_u32 s6, 64
	s_cbranch_scc0 .Lei_8
	buffer_inv sc1

; __device__ __forceinline__ unsigned xb_add(unsigned* p, unsigned v) { return __hip_atomic_fetch_add(p, v, __ATOMIC_RELAXED, __HIP_MEMORY_SCOPE_AGENT); }
; __device__ __forceinline__ void xcd_barrier(const XcdBarrier& b, int tid) {
;     asm volatile("s_waitcnt vmcnt(0)" ::: "memory");
;     __syncthreads();
;     if (tid == 0) {
;         unsigned* bar = b.bar;
;         __builtin_amdgcn_s_waitcnt(0);
;         unsigned nloc = b.st[0], nx = b.st[1];
;         if (nloc == 0u) { xcd_barrier_complete(bar, b.x, nloc, nx); b.st[0] = nloc; b.st[1] = nx; }
;         const unsigned old = xb_add(&bar[XB_XSUB(b.x)], 1u);
;         const unsigned gen = old / nloc;
;         if (old + 1u == (gen + 1u) * nloc) {
;             __builtin_amdgcn_fence(__ATOMIC_RELEASE, "agent");
.Lgs_orig_5:
	v_readlane_b32 s100, v255, 8
	s_cmp_eq_u32 s100, 2
	s_cbranch_scc0 .Lp3_orig_1
	v_readfirstlane_b32 s6, v215
	s_cmp_lt_u32 s6, 64
	s_cbranch_scc0 .Lei_9
	buffer_inv sc1
